# hgrn_scan (workgroups 0..31): inputs streamed once with wide discarded loads before the serial scan loop so its per-chunk loads hit L2
# speedup vs baseline: 1.0060x; 1.0060x over previous
.LBB0_335:
	s_andn2_b64 vcc, exec, s[10:11]
	s_cbranch_vccnz .LBB0_338
	s_load_dwordx2 s[6:7], s[16:17], 0xe0
	v_readlane_b32 s1, v254, 0
	s_waitcnt lgkmcnt(0)
	s_lshl_b32 s42, s2, 11
	s_add_u32 s42, s6, s42
	s_addc_u32 s43, s7, 0
	s_add_u32 s42, s42, 0x4000000
	s_addc_u32 s43, s43, 0
	v_and_b32_e32 v140, 0x7f, v72
	v_lshlrev_b32_e32 v140, 4, v140
	v_lshrrev_b32_e32 v141, 7, v72
	v_lshl_add_u32 v140, v141, 16, v140
	s_movk_i32 s48, 32
.Lpf_hu:
	global_load_dwordx4 v[144:147], v140, s[42:43]
	s_add_u32 s42, s42, 0x40000
	s_addc_u32 s43, s43, 0
	s_sub_u32 s48, s48, 1
	s_cmp_lg_u32 s48, 0
	s_cbranch_scc1 .Lpf_hu
	s_lshl_b32 s42, s2, 5
	s_add_u32 s42, s6, s42
	s_addc_u32 s43, s7, 0
	s_add_u32 s42, s42, 0xf000000
	s_addc_u32 s43, s43, 0
	v_and_b32_e32 v141, 0xff, v72
	v_lshrrev_b32_e32 v142, 1, v141
	v_and_b32_e32 v141, 1, v141
	v_lshlrev_b32_e32 v141, 4, v141
	v_lshl_add_u32 v140, v142, 10, v141
	global_load_dwordx4 v[144:147], v140, s[42:43]
	s_add_u32 s10, s6, 0xf000000
	v_add_u32_e32 v2, s1, v72
	v_ashrrev_i32_e32 v3, 31, v2
	v_lshrrev_b32_e32 v4, 6, v2
	v_lshl_add_u64 v[0:1], v[2:3], 2, s[6:7]
	s_addc_u32 s11, s7, 0
	s_mov_b64 s[6:7], 0x4000000
	v_ashrrev_i32_e32 v2, 6, v2
	s_movk_i32 s1, 0xffc0
	v_lshl_add_u64 v[0:1], v[0:1], 0, s[6:7]
	v_bfi_b32 v2, s1, v2, v4
	v_mov_b32_e32 v4, 0
	s_movk_i32 s6, 0xffe0
